# W_o phase below the last layer: one-tile CUs start their residual epilogue ~16 us late so the 32 two-tile CUs are served first
# speedup vs baseline: 1.0039x; 1.0039x over previous
; #define PG8_BAR __builtin_amdgcn_s_barrier()
;     ...
;         if (wr == 0) PG8_BAR;
;         E(acc, cur, wr, wc, fr, fq);
; DI void phase_g4(const Frame& F) {
;     const unsigned char* W = F.ws + WS_W; const int nM = (F.l == NL - 1 ? ML : MT) / 256;
;     pg8::Sched2 S; S.tileBytes = 256L * 1024 * 2; S.G = F.G; S.c = F.bid;
;     S.j0 = pg8::JobD{(const char*)(F.ws + WS_HB), (const char*)(W + W_O), nM, 4, 1, 0, 0}; S.j1 = S.j0; S.n0 = nM * 4; S.total = S.n0;
;     EpiRes E{F, 2, true, F.l > 0 ? 2 : 0};
;     pg8::gemm_phase(F.lds, 1024, S, E, F.tid);
; }
.LBB0_142:
	s_cmp_lt_u32 s96, 32
	s_cbranch_scc1 .Lg4_nodelay
	v_readlane_b32 s5, v255, 35
	s_cmp_eq_u32 s5, 3
	s_cbranch_scc1 .Lg4_nodelay
	s_sleep 127
	s_sleep 127
	s_sleep 127
	s_sleep 127
